# y pair sums of two steps written by one ds_write2_b32
# speedup vs baseline: 1.0046x; 1.0046x over previous
.LBB0_682:
	s_bitcmp1_b32 s30, 0
	s_cselect_b32 s6, 0xe000, 0
	s_add_i32 s6, s6, 0
	v_add_u32_e32 v90, s6, v58
	v_sub_u32_e32 v88, v90, v61
	v_add_u32_e32 v89, s6, v86
	ds_read_b128 v[4:7], v90 offset:0x4000
	ds_read_b128 v[8:11], v90 offset:0x0
	ds_read2st64_b32 v[108:109], v89 offset0:192 offset1:193
	ds_read2st64_b64 v[100:103], v88 offset0:64 offset1:65
	ds_read_b128 v[112:115], v90 offset:0x4200
	ds_read_b128 v[96:99], v90 offset:0x200
	v_mov_b32_e32 v93, v91
	s_waitcnt lgkmcnt(3)
	v_pk_mul_f32 v[0:1], v[52:53], v[4:5] op_sel_hi:[0,1]
	v_pk_fma_f32 v[0:1], v[52:53], v[6:7], v[0:1] op_sel:[1,0,0]
	v_pk_mul_f32 v[10:11], v[108:109], v[10:11] op_sel_hi:[0,1]
	ds_read_b128 v[4:7], v90 offset:0x4400
	v_add_f32_dpp v0, v0, v0 quad_perm:[1,0,3,2] row_mask:0xf bank_mask:0xf bound_ctrl:1
	v_add_f32_dpp v1, v1, v1 quad_perm:[1,0,3,2] row_mask:0xf bank_mask:0xf bound_ctrl:1
	v_pk_fma_f32 v[54:55], v[52:53], v[8:9], v[10:11]
	v_add_f32_dpp v0, v0, v0 quad_perm:[2,3,0,1] row_mask:0xf bank_mask:0xf bound_ctrl:1
	ds_read_b128 v[8:11], v90 offset:0x400
	s_nop 0
	v_add_f32_dpp v0, v0, v0 row_half_mirror row_mask:0xf bank_mask:0xf bound_ctrl:1
	s_nop 0
	s_nop 0
	v_add_f32_dpp v2, v0, v0 row_mirror row_mask:0xf bank_mask:0xf bound_ctrl:1
	v_add_f32_dpp v0, v0, v0 row_mirror row_mask:0xf bank_mask:0xf bound_ctrl:1
	ds_read2st64_b32 v[110:111], v89 offset0:194 offset1:195
	s_waitcnt lgkmcnt(3)
	v_permlane16_swap_b32_e32 v0, v2
	v_add_f32_e32 v0, v0, v2
	v_pk_fma_f32 v[52:53], v[100:101], v[0:1], v[54:55] op_sel_hi:[1,0,1]
	v_pk_mul_f32 v[118:119], v[52:53], v[112:113] op_sel_hi:[0,1]
	v_pk_fma_f32 v[118:119], v[52:53], v[114:115], v[118:119] op_sel:[1,0,0]
	v_pk_mul_f32 v[98:99], v[108:109], v[98:99] op_sel:[1,0]
	ds_read_b128 v[112:115], v90 offset:0x4600
	v_add_f32_dpp v118, v118, v118 quad_perm:[1,0,3,2] row_mask:0xf bank_mask:0xf bound_ctrl:1
	v_add_f32_dpp v119, v119, v119 quad_perm:[1,0,3,2] row_mask:0xf bank_mask:0xf bound_ctrl:1
	v_pk_fma_f32 v[54:55], v[52:53], v[96:97], v[98:99]
	v_add_f32_dpp v118, v118, v118 quad_perm:[2,3,0,1] row_mask:0xf bank_mask:0xf bound_ctrl:1
	ds_read_b128 v[96:99], v90 offset:0x600
	s_nop 0
	v_add_f32_dpp v118, v118, v118 row_half_mirror row_mask:0xf bank_mask:0xf bound_ctrl:1
	ds_write2_b32 v93, v1, v119 offset0:0 offset1:36
	s_nop 0
	v_add_f32_dpp v2, v118, v118 row_mirror row_mask:0xf bank_mask:0xf bound_ctrl:1
	v_add_f32_dpp v118, v118, v118 row_mirror row_mask:0xf bank_mask:0xf bound_ctrl:1
	ds_read2st64_b64 v[104:107], v88 offset0:66 offset1:67
	s_waitcnt lgkmcnt(4)
	v_permlane16_swap_b32_e32 v118, v2
	v_add_f32_e32 v118, v118, v2
	v_pk_fma_f32 v[52:53], v[102:103], v[118:119], v[54:55] op_sel_hi:[1,0,1]
	v_pk_mul_f32 v[0:1], v[52:53], v[4:5] op_sel_hi:[0,1]
	v_pk_fma_f32 v[0:1], v[52:53], v[6:7], v[0:1] op_sel:[1,0,0]
	v_pk_mul_f32 v[10:11], v[110:111], v[10:11] op_sel_hi:[0,1]
	ds_read_b128 v[4:7], v90 offset:0x4800
	v_add_f32_dpp v0, v0, v0 quad_perm:[1,0,3,2] row_mask:0xf bank_mask:0xf bound_ctrl:1
	v_add_f32_dpp v1, v1, v1 quad_perm:[1,0,3,2] row_mask:0xf bank_mask:0xf bound_ctrl:1
	v_pk_fma_f32 v[54:55], v[52:53], v[8:9], v[10:11]
	v_add_f32_dpp v0, v0, v0 quad_perm:[2,3,0,1] row_mask:0xf bank_mask:0xf bound_ctrl:1
	ds_read_b128 v[8:11], v90 offset:0x800
	s_nop 0
	v_add_f32_dpp v0, v0, v0 row_half_mirror row_mask:0xf bank_mask:0xf bound_ctrl:1
	s_nop 0
	s_nop 0
	v_add_f32_dpp v2, v0, v0 row_mirror row_mask:0xf bank_mask:0xf bound_ctrl:1
	v_add_f32_dpp v0, v0, v0 row_mirror row_mask:0xf bank_mask:0xf bound_ctrl:1
	ds_read2st64_b32 v[108:109], v89 offset0:196 offset1:197
	s_waitcnt lgkmcnt(3)
	v_permlane16_swap_b32_e32 v0, v2
	v_add_f32_e32 v0, v0, v2
	v_pk_fma_f32 v[52:53], v[104:105], v[0:1], v[54:55] op_sel_hi:[1,0,1]
	v_pk_mul_f32 v[118:119], v[52:53], v[112:113] op_sel_hi:[0,1]
	v_pk_fma_f32 v[118:119], v[52:53], v[114:115], v[118:119] op_sel:[1,0,0]
	v_pk_mul_f32 v[98:99], v[110:111], v[98:99] op_sel:[1,0]
	ds_read_b128 v[112:115], v90 offset:0x4a00
	v_add_f32_dpp v118, v118, v118 quad_perm:[1,0,3,2] row_mask:0xf bank_mask:0xf bound_ctrl:1
	v_add_f32_dpp v119, v119, v119 quad_perm:[1,0,3,2] row_mask:0xf bank_mask:0xf bound_ctrl:1
	v_pk_fma_f32 v[54:55], v[52:53], v[96:97], v[98:99]
	v_add_f32_dpp v118, v118, v118 quad_perm:[2,3,0,1] row_mask:0xf bank_mask:0xf bound_ctrl:1
	ds_read_b128 v[96:99], v90 offset:0xa00
	s_nop 0
	v_add_f32_dpp v118, v118, v118 row_half_mirror row_mask:0xf bank_mask:0xf bound_ctrl:1
	ds_write2_b32 v93, v1, v119 offset0:72 offset1:108
	s_nop 0
	v_add_f32_dpp v2, v118, v118 row_mirror row_mask:0xf bank_mask:0xf bound_ctrl:1
	v_add_f32_dpp v118, v118, v118 row_mirror row_mask:0xf bank_mask:0xf bound_ctrl:1
	ds_read2st64_b64 v[100:103], v88 offset0:68 offset1:69
	s_waitcnt lgkmcnt(4)
	v_permlane16_swap_b32_e32 v118, v2
	v_add_f32_e32 v118, v118, v2
	v_pk_fma_f32 v[52:53], v[106:107], v[118:119], v[54:55] op_sel_hi:[1,0,1]
	v_pk_mul_f32 v[0:1], v[52:53], v[4:5] op_sel_hi:[0,1]
	v_pk_fma_f32 v[0:1], v[52:53], v[6:7], v[0:1] op_sel:[1,0,0]
	v_pk_mul_f32 v[10:11], v[108:109], v[10:11] op_sel_hi:[0,1]
	ds_read_b128 v[4:7], v90 offset:0x4c00
	v_add_f32_dpp v0, v0, v0 quad_perm:[1,0,3,2] row_mask:0xf bank_mask:0xf bound_ctrl:1
	v_add_f32_dpp v1, v1, v1 quad_perm:[1,0,3,2] row_mask:0xf bank_mask:0xf bound_ctrl:1
	v_pk_fma_f32 v[54:55], v[52:53], v[8:9], v[10:11]
	v_add_f32_dpp v0, v0, v0 quad_perm:[2,3,0,1] row_mask:0xf bank_mask:0xf bound_ctrl:1
	ds_read_b128 v[8:11], v90 offset:0xc00
	s_nop 0
	v_add_f32_dpp v0, v0, v0 row_half_mirror row_mask:0xf bank_mask:0xf bound_ctrl:1
	s_nop 0
	s_nop 0
	v_add_f32_dpp v2, v0, v0 row_mirror row_mask:0xf bank_mask:0xf bound_ctrl:1
	v_add_f32_dpp v0, v0, v0 row_mirror row_mask:0xf bank_mask:0xf bound_ctrl:1
	ds_read2st64_b32 v[110:111], v89 offset0:198 offset1:199
	s_waitcnt lgkmcnt(3)
	v_permlane16_swap_b32_e32 v0, v2
	v_add_f32_e32 v0, v0, v2
	v_pk_fma_f32 v[52:53], v[100:101], v[0:1], v[54:55] op_sel_hi:[1,0,1]
	v_pk_mul_f32 v[118:119], v[52:53], v[112:113] op_sel_hi:[0,1]
	v_pk_fma_f32 v[118:119], v[52:53], v[114:115], v[118:119] op_sel:[1,0,0]
	v_pk_mul_f32 v[98:99], v[108:109], v[98:99] op_sel:[1,0]
	ds_read_b128 v[112:115], v90 offset:0x4e00
	v_add_f32_dpp v118, v118, v118 quad_perm:[1,0,3,2] row_mask:0xf bank_mask:0xf bound_ctrl:1
	v_add_f32_dpp v119, v119, v119 quad_perm:[1,0,3,2] row_mask:0xf bank_mask:0xf bound_ctrl:1
	v_pk_fma_f32 v[54:55], v[52:53], v[96:97], v[98:99]
	v_add_f32_dpp v118, v118, v118 quad_perm:[2,3,0,1] row_mask:0xf bank_mask:0xf bound_ctrl:1
	ds_read_b128 v[96:99], v90 offset:0xe00
	s_nop 0
	v_add_f32_dpp v118, v118, v118 row_half_mirror row_mask:0xf bank_mask:0xf bound_ctrl:1
	ds_write2_b32 v93, v1, v119 offset0:144 offset1:180
	s_nop 0
	v_add_f32_dpp v2, v118, v118 row_mirror row_mask:0xf bank_mask:0xf bound_ctrl:1
	v_add_f32_dpp v118, v118, v118 row_mirror row_mask:0xf bank_mask:0xf bound_ctrl:1
	ds_read2st64_b64 v[104:107], v88 offset0:70 offset1:71
	s_waitcnt lgkmcnt(4)
	v_permlane16_swap_b32_e32 v118, v2
	v_add_f32_e32 v118, v118, v2
	v_pk_fma_f32 v[52:53], v[102:103], v[118:119], v[54:55] op_sel_hi:[1,0,1]
	v_pk_mul_f32 v[0:1], v[52:53], v[4:5] op_sel_hi:[0,1]
	v_pk_fma_f32 v[0:1], v[52:53], v[6:7], v[0:1] op_sel:[1,0,0]
	v_pk_mul_f32 v[10:11], v[110:111], v[10:11] op_sel_hi:[0,1]
	ds_read_b128 v[4:7], v90 offset:0x5000
	v_add_f32_dpp v0, v0, v0 quad_perm:[1,0,3,2] row_mask:0xf bank_mask:0xf bound_ctrl:1
	v_add_f32_dpp v1, v1, v1 quad_perm:[1,0,3,2] row_mask:0xf bank_mask:0xf bound_ctrl:1
	v_pk_fma_f32 v[54:55], v[52:53], v[8:9], v[10:11]
	v_add_f32_dpp v0, v0, v0 quad_perm:[2,3,0,1] row_mask:0xf bank_mask:0xf bound_ctrl:1
	ds_read_b128 v[8:11], v90 offset:0x1000
	s_nop 0
	v_add_f32_dpp v0, v0, v0 row_half_mirror row_mask:0xf bank_mask:0xf bound_ctrl:1
	s_nop 0
	s_nop 0
	v_add_f32_dpp v2, v0, v0 row_mirror row_mask:0xf bank_mask:0xf bound_ctrl:1
	v_add_f32_dpp v0, v0, v0 row_mirror row_mask:0xf bank_mask:0xf bound_ctrl:1
	ds_read2st64_b32 v[108:109], v89 offset0:200 offset1:201
	s_waitcnt lgkmcnt(3)
	v_permlane16_swap_b32_e32 v0, v2
	v_add_f32_e32 v0, v0, v2
	v_pk_fma_f32 v[52:53], v[104:105], v[0:1], v[54:55] op_sel_hi:[1,0,1]
	v_pk_mul_f32 v[118:119], v[52:53], v[112:113] op_sel_hi:[0,1]
	v_pk_fma_f32 v[118:119], v[52:53], v[114:115], v[118:119] op_sel:[1,0,0]
	v_pk_mul_f32 v[98:99], v[110:111], v[98:99] op_sel:[1,0]
	ds_read_b128 v[112:115], v90 offset:0x5200
	v_add_f32_dpp v118, v118, v118 quad_perm:[1,0,3,2] row_mask:0xf bank_mask:0xf bound_ctrl:1
	v_add_f32_dpp v119, v119, v119 quad_perm:[1,0,3,2] row_mask:0xf bank_mask:0xf bound_ctrl:1
	v_pk_fma_f32 v[54:55], v[52:53], v[96:97], v[98:99]
	v_add_f32_dpp v118, v118, v118 quad_perm:[2,3,0,1] row_mask:0xf bank_mask:0xf bound_ctrl:1
	ds_read_b128 v[96:99], v90 offset:0x1200
	s_nop 0
	v_add_f32_dpp v118, v118, v118 row_half_mirror row_mask:0xf bank_mask:0xf bound_ctrl:1
	ds_write2_b32 v93, v1, v119 offset0:216 offset1:252
	s_nop 0
	v_add_f32_dpp v2, v118, v118 row_mirror row_mask:0xf bank_mask:0xf bound_ctrl:1
	v_add_f32_dpp v118, v118, v118 row_mirror row_mask:0xf bank_mask:0xf bound_ctrl:1
	ds_read2st64_b64 v[100:103], v88 offset0:72 offset1:73
	s_waitcnt lgkmcnt(4)
	v_permlane16_swap_b32_e32 v118, v2
	v_add_f32_e32 v118, v118, v2
	v_pk_fma_f32 v[52:53], v[106:107], v[118:119], v[54:55] op_sel_hi:[1,0,1]
	v_pk_mul_f32 v[0:1], v[52:53], v[4:5] op_sel_hi:[0,1]
	v_pk_fma_f32 v[0:1], v[52:53], v[6:7], v[0:1] op_sel:[1,0,0]
	v_pk_mul_f32 v[10:11], v[108:109], v[10:11] op_sel_hi:[0,1]
	ds_read_b128 v[4:7], v90 offset:0x5400
	v_add_f32_dpp v0, v0, v0 quad_perm:[1,0,3,2] row_mask:0xf bank_mask:0xf bound_ctrl:1
	v_add_f32_dpp v1, v1, v1 quad_perm:[1,0,3,2] row_mask:0xf bank_mask:0xf bound_ctrl:1
	v_pk_fma_f32 v[54:55], v[52:53], v[8:9], v[10:11]
	v_add_f32_dpp v0, v0, v0 quad_perm:[2,3,0,1] row_mask:0xf bank_mask:0xf bound_ctrl:1
	ds_read_b128 v[8:11], v90 offset:0x1400
	s_nop 0
	v_add_f32_dpp v0, v0, v0 row_half_mirror row_mask:0xf bank_mask:0xf bound_ctrl:1
	v_add_u32_e32 v93, 0x480, v93
	s_nop 0
	v_add_f32_dpp v2, v0, v0 row_mirror row_mask:0xf bank_mask:0xf bound_ctrl:1
	v_add_f32_dpp v0, v0, v0 row_mirror row_mask:0xf bank_mask:0xf bound_ctrl:1
	ds_read2st64_b32 v[110:111], v89 offset0:202 offset1:203
	s_waitcnt lgkmcnt(3)
	v_permlane16_swap_b32_e32 v0, v2
	v_add_f32_e32 v0, v0, v2
	v_pk_fma_f32 v[52:53], v[100:101], v[0:1], v[54:55] op_sel_hi:[1,0,1]
	v_pk_mul_f32 v[118:119], v[52:53], v[112:113] op_sel_hi:[0,1]
	v_pk_fma_f32 v[118:119], v[52:53], v[114:115], v[118:119] op_sel:[1,0,0]
	v_pk_mul_f32 v[98:99], v[108:109], v[98:99] op_sel:[1,0]
	ds_read_b128 v[112:115], v90 offset:0x5600
	v_add_f32_dpp v118, v118, v118 quad_perm:[1,0,3,2] row_mask:0xf bank_mask:0xf bound_ctrl:1
	v_add_f32_dpp v119, v119, v119 quad_perm:[1,0,3,2] row_mask:0xf bank_mask:0xf bound_ctrl:1
	v_pk_fma_f32 v[54:55], v[52:53], v[96:97], v[98:99]
	v_add_f32_dpp v118, v118, v118 quad_perm:[2,3,0,1] row_mask:0xf bank_mask:0xf bound_ctrl:1
	ds_read_b128 v[96:99], v90 offset:0x1600
	s_nop 0
	v_add_f32_dpp v118, v118, v118 row_half_mirror row_mask:0xf bank_mask:0xf bound_ctrl:1
	ds_write2_b32 v93, v1, v119 offset0:0 offset1:36
	s_nop 0
	v_add_f32_dpp v2, v118, v118 row_mirror row_mask:0xf bank_mask:0xf bound_ctrl:1
	v_add_f32_dpp v118, v118, v118 row_mirror row_mask:0xf bank_mask:0xf bound_ctrl:1
	ds_read2st64_b64 v[104:107], v88 offset0:74 offset1:75
	s_waitcnt lgkmcnt(4)
	v_permlane16_swap_b32_e32 v118, v2
	v_add_f32_e32 v118, v118, v2
	v_pk_fma_f32 v[52:53], v[102:103], v[118:119], v[54:55] op_sel_hi:[1,0,1]
	v_pk_mul_f32 v[0:1], v[52:53], v[4:5] op_sel_hi:[0,1]
	v_pk_fma_f32 v[0:1], v[52:53], v[6:7], v[0:1] op_sel:[1,0,0]
	v_pk_mul_f32 v[10:11], v[110:111], v[10:11] op_sel_hi:[0,1]
	ds_read_b128 v[4:7], v90 offset:0x5800
	v_add_f32_dpp v0, v0, v0 quad_perm:[1,0,3,2] row_mask:0xf bank_mask:0xf bound_ctrl:1
	v_add_f32_dpp v1, v1, v1 quad_perm:[1,0,3,2] row_mask:0xf bank_mask:0xf bound_ctrl:1
	v_pk_fma_f32 v[54:55], v[52:53], v[8:9], v[10:11]
	v_add_f32_dpp v0, v0, v0 quad_perm:[2,3,0,1] row_mask:0xf bank_mask:0xf bound_ctrl:1
	ds_read_b128 v[8:11], v90 offset:0x1800
	s_nop 0
	v_add_f32_dpp v0, v0, v0 row_half_mirror row_mask:0xf bank_mask:0xf bound_ctrl:1
	s_nop 0
	s_nop 0
	v_add_f32_dpp v2, v0, v0 row_mirror row_mask:0xf bank_mask:0xf bound_ctrl:1
	v_add_f32_dpp v0, v0, v0 row_mirror row_mask:0xf bank_mask:0xf bound_ctrl:1
	ds_read2st64_b32 v[108:109], v89 offset0:204 offset1:205
	s_waitcnt lgkmcnt(3)
	v_permlane16_swap_b32_e32 v0, v2
	v_add_f32_e32 v0, v0, v2
	v_pk_fma_f32 v[52:53], v[104:105], v[0:1], v[54:55] op_sel_hi:[1,0,1]
	v_pk_mul_f32 v[118:119], v[52:53], v[112:113] op_sel_hi:[0,1]
	v_pk_fma_f32 v[118:119], v[52:53], v[114:115], v[118:119] op_sel:[1,0,0]
	v_pk_mul_f32 v[98:99], v[110:111], v[98:99] op_sel:[1,0]
	ds_read_b128 v[112:115], v90 offset:0x5a00
	v_add_f32_dpp v118, v118, v118 quad_perm:[1,0,3,2] row_mask:0xf bank_mask:0xf bound_ctrl:1
	v_add_f32_dpp v119, v119, v119 quad_perm:[1,0,3,2] row_mask:0xf bank_mask:0xf bound_ctrl:1
	v_pk_fma_f32 v[54:55], v[52:53], v[96:97], v[98:99]
	v_add_f32_dpp v118, v118, v118 quad_perm:[2,3,0,1] row_mask:0xf bank_mask:0xf bound_ctrl:1
	ds_read_b128 v[96:99], v90 offset:0x1a00
	s_nop 0
	v_add_f32_dpp v118, v118, v118 row_half_mirror row_mask:0xf bank_mask:0xf bound_ctrl:1
	ds_write2_b32 v93, v1, v119 offset0:72 offset1:108
	s_nop 0
	v_add_f32_dpp v2, v118, v118 row_mirror row_mask:0xf bank_mask:0xf bound_ctrl:1
	v_add_f32_dpp v118, v118, v118 row_mirror row_mask:0xf bank_mask:0xf bound_ctrl:1
	ds_read2st64_b64 v[100:103], v88 offset0:76 offset1:77
	s_waitcnt lgkmcnt(4)
	v_permlane16_swap_b32_e32 v118, v2
	v_add_f32_e32 v118, v118, v2
	v_pk_fma_f32 v[52:53], v[106:107], v[118:119], v[54:55] op_sel_hi:[1,0,1]
	v_pk_mul_f32 v[0:1], v[52:53], v[4:5] op_sel_hi:[0,1]
	v_pk_fma_f32 v[0:1], v[52:53], v[6:7], v[0:1] op_sel:[1,0,0]
	v_pk_mul_f32 v[10:11], v[108:109], v[10:11] op_sel_hi:[0,1]
	ds_read_b128 v[4:7], v90 offset:0x5c00
	v_add_f32_dpp v0, v0, v0 quad_perm:[1,0,3,2] row_mask:0xf bank_mask:0xf bound_ctrl:1
	v_add_f32_dpp v1, v1, v1 quad_perm:[1,0,3,2] row_mask:0xf bank_mask:0xf bound_ctrl:1
	v_pk_fma_f32 v[54:55], v[52:53], v[8:9], v[10:11]
	v_add_f32_dpp v0, v0, v0 quad_perm:[2,3,0,1] row_mask:0xf bank_mask:0xf bound_ctrl:1
	ds_read_b128 v[8:11], v90 offset:0x1c00
	s_nop 0
	v_add_f32_dpp v0, v0, v0 row_half_mirror row_mask:0xf bank_mask:0xf bound_ctrl:1
	s_nop 0
	s_nop 0
	v_add_f32_dpp v2, v0, v0 row_mirror row_mask:0xf bank_mask:0xf bound_ctrl:1
	v_add_f32_dpp v0, v0, v0 row_mirror row_mask:0xf bank_mask:0xf bound_ctrl:1
	ds_read2st64_b32 v[110:111], v89 offset0:206 offset1:207
	s_waitcnt lgkmcnt(3)
	v_permlane16_swap_b32_e32 v0, v2
	v_add_f32_e32 v0, v0, v2
	v_pk_fma_f32 v[52:53], v[100:101], v[0:1], v[54:55] op_sel_hi:[1,0,1]
	v_pk_mul_f32 v[118:119], v[52:53], v[112:113] op_sel_hi:[0,1]
	v_pk_fma_f32 v[118:119], v[52:53], v[114:115], v[118:119] op_sel:[1,0,0]
	v_pk_mul_f32 v[98:99], v[108:109], v[98:99] op_sel:[1,0]
	ds_read_b128 v[112:115], v90 offset:0x5e00
	v_add_f32_dpp v118, v118, v118 quad_perm:[1,0,3,2] row_mask:0xf bank_mask:0xf bound_ctrl:1
	v_add_f32_dpp v119, v119, v119 quad_perm:[1,0,3,2] row_mask:0xf bank_mask:0xf bound_ctrl:1
	v_pk_fma_f32 v[54:55], v[52:53], v[96:97], v[98:99]
	v_add_f32_dpp v118, v118, v118 quad_perm:[2,3,0,1] row_mask:0xf bank_mask:0xf bound_ctrl:1
	ds_read_b128 v[96:99], v90 offset:0x1e00
	s_nop 0
	v_add_f32_dpp v118, v118, v118 row_half_mirror row_mask:0xf bank_mask:0xf bound_ctrl:1
	ds_write2_b32 v93, v1, v119 offset0:144 offset1:180
	s_nop 0
	v_add_f32_dpp v2, v118, v118 row_mirror row_mask:0xf bank_mask:0xf bound_ctrl:1
	v_add_f32_dpp v118, v118, v118 row_mirror row_mask:0xf bank_mask:0xf bound_ctrl:1
	ds_read2st64_b64 v[104:107], v88 offset0:78 offset1:79
	s_waitcnt lgkmcnt(4)
	v_permlane16_swap_b32_e32 v118, v2
	v_add_f32_e32 v118, v118, v2
	v_pk_fma_f32 v[52:53], v[102:103], v[118:119], v[54:55] op_sel_hi:[1,0,1]
	v_pk_mul_f32 v[0:1], v[52:53], v[4:5] op_sel_hi:[0,1]
	v_pk_fma_f32 v[0:1], v[52:53], v[6:7], v[0:1] op_sel:[1,0,0]
	v_pk_mul_f32 v[10:11], v[110:111], v[10:11] op_sel_hi:[0,1]
	ds_read_b128 v[4:7], v90 offset:0x6000
	v_add_f32_dpp v0, v0, v0 quad_perm:[1,0,3,2] row_mask:0xf bank_mask:0xf bound_ctrl:1
	v_add_f32_dpp v1, v1, v1 quad_perm:[1,0,3,2] row_mask:0xf bank_mask:0xf bound_ctrl:1
	v_pk_fma_f32 v[54:55], v[52:53], v[8:9], v[10:11]
	v_add_f32_dpp v0, v0, v0 quad_perm:[2,3,0,1] row_mask:0xf bank_mask:0xf bound_ctrl:1
	ds_read_b128 v[8:11], v90 offset:0x2000
	s_nop 0
	v_add_f32_dpp v0, v0, v0 row_half_mirror row_mask:0xf bank_mask:0xf bound_ctrl:1
	s_nop 0
	s_nop 0
	v_add_f32_dpp v2, v0, v0 row_mirror row_mask:0xf bank_mask:0xf bound_ctrl:1
	v_add_f32_dpp v0, v0, v0 row_mirror row_mask:0xf bank_mask:0xf bound_ctrl:1
	ds_read2st64_b32 v[108:109], v89 offset0:208 offset1:209
	s_waitcnt lgkmcnt(3)
	v_permlane16_swap_b32_e32 v0, v2
	v_add_f32_e32 v0, v0, v2
	v_pk_fma_f32 v[52:53], v[104:105], v[0:1], v[54:55] op_sel_hi:[1,0,1]
	v_pk_mul_f32 v[118:119], v[52:53], v[112:113] op_sel_hi:[0,1]
	v_pk_fma_f32 v[118:119], v[52:53], v[114:115], v[118:119] op_sel:[1,0,0]
	v_pk_mul_f32 v[98:99], v[110:111], v[98:99] op_sel:[1,0]
	ds_read_b128 v[112:115], v90 offset:0x6200
	v_add_f32_dpp v118, v118, v118 quad_perm:[1,0,3,2] row_mask:0xf bank_mask:0xf bound_ctrl:1
	v_add_f32_dpp v119, v119, v119 quad_perm:[1,0,3,2] row_mask:0xf bank_mask:0xf bound_ctrl:1
	v_pk_fma_f32 v[54:55], v[52:53], v[96:97], v[98:99]
	v_add_f32_dpp v118, v118, v118 quad_perm:[2,3,0,1] row_mask:0xf bank_mask:0xf bound_ctrl:1
	ds_read_b128 v[96:99], v90 offset:0x2200
	s_nop 0
	v_add_f32_dpp v118, v118, v118 row_half_mirror row_mask:0xf bank_mask:0xf bound_ctrl:1
	ds_write2_b32 v93, v1, v119 offset0:216 offset1:252
	s_nop 0
	v_add_f32_dpp v2, v118, v118 row_mirror row_mask:0xf bank_mask:0xf bound_ctrl:1
	v_add_f32_dpp v118, v118, v118 row_mirror row_mask:0xf bank_mask:0xf bound_ctrl:1
	ds_read2st64_b64 v[100:103], v88 offset0:80 offset1:81
	s_waitcnt lgkmcnt(4)
	v_permlane16_swap_b32_e32 v118, v2
	v_add_f32_e32 v118, v118, v2
	v_pk_fma_f32 v[52:53], v[106:107], v[118:119], v[54:55] op_sel_hi:[1,0,1]
	s_cmp_eq_u32 s88, 0x800000
	s_cbranch_scc1 .LBB0_684
	v_pk_mul_f32 v[0:1], v[52:53], v[4:5] op_sel_hi:[0,1]
	v_pk_fma_f32 v[0:1], v[52:53], v[6:7], v[0:1] op_sel:[1,0,0]
	v_pk_mul_f32 v[10:11], v[108:109], v[10:11] op_sel_hi:[0,1]
	ds_read_b128 v[4:7], v90 offset:0x6400
	v_add_f32_dpp v0, v0, v0 quad_perm:[1,0,3,2] row_mask:0xf bank_mask:0xf bound_ctrl:1
	v_add_f32_dpp v1, v1, v1 quad_perm:[1,0,3,2] row_mask:0xf bank_mask:0xf bound_ctrl:1
	v_pk_fma_f32 v[54:55], v[52:53], v[8:9], v[10:11]
	v_add_f32_dpp v0, v0, v0 quad_perm:[2,3,0,1] row_mask:0xf bank_mask:0xf bound_ctrl:1
	ds_read_b128 v[8:11], v90 offset:0x2400
	s_nop 0
	v_add_f32_dpp v0, v0, v0 row_half_mirror row_mask:0xf bank_mask:0xf bound_ctrl:1
	v_add_u32_e32 v93, 0x480, v93
	s_nop 0
	v_add_f32_dpp v2, v0, v0 row_mirror row_mask:0xf bank_mask:0xf bound_ctrl:1
	v_add_f32_dpp v0, v0, v0 row_mirror row_mask:0xf bank_mask:0xf bound_ctrl:1
	ds_read2st64_b32 v[110:111], v89 offset0:210 offset1:211
	s_waitcnt lgkmcnt(3)
	v_permlane16_swap_b32_e32 v0, v2
	v_add_f32_e32 v0, v0, v2
	v_pk_fma_f32 v[52:53], v[100:101], v[0:1], v[54:55] op_sel_hi:[1,0,1]
	v_pk_mul_f32 v[118:119], v[52:53], v[112:113] op_sel_hi:[0,1]
	v_pk_fma_f32 v[118:119], v[52:53], v[114:115], v[118:119] op_sel:[1,0,0]
	v_pk_mul_f32 v[98:99], v[108:109], v[98:99] op_sel:[1,0]
	ds_read_b128 v[112:115], v90 offset:0x6600
	v_add_f32_dpp v118, v118, v118 quad_perm:[1,0,3,2] row_mask:0xf bank_mask:0xf bound_ctrl:1
	v_add_f32_dpp v119, v119, v119 quad_perm:[1,0,3,2] row_mask:0xf bank_mask:0xf bound_ctrl:1
	v_pk_fma_f32 v[54:55], v[52:53], v[96:97], v[98:99]
	v_add_f32_dpp v118, v118, v118 quad_perm:[2,3,0,1] row_mask:0xf bank_mask:0xf bound_ctrl:1
	ds_read_b128 v[96:99], v90 offset:0x2600
	s_nop 0
	v_add_f32_dpp v118, v118, v118 row_half_mirror row_mask:0xf bank_mask:0xf bound_ctrl:1
	ds_write2_b32 v93, v1, v119 offset0:0 offset1:36
	s_nop 0
	v_add_f32_dpp v2, v118, v118 row_mirror row_mask:0xf bank_mask:0xf bound_ctrl:1
	v_add_f32_dpp v118, v118, v118 row_mirror row_mask:0xf bank_mask:0xf bound_ctrl:1
	ds_read2st64_b64 v[104:107], v88 offset0:82 offset1:83
	s_waitcnt lgkmcnt(4)
	v_permlane16_swap_b32_e32 v118, v2
	v_add_f32_e32 v118, v118, v2
	v_pk_fma_f32 v[52:53], v[102:103], v[118:119], v[54:55] op_sel_hi:[1,0,1]
	v_pk_mul_f32 v[0:1], v[52:53], v[4:5] op_sel_hi:[0,1]
	v_pk_fma_f32 v[0:1], v[52:53], v[6:7], v[0:1] op_sel:[1,0,0]
	v_pk_mul_f32 v[10:11], v[110:111], v[10:11] op_sel_hi:[0,1]
	ds_read_b128 v[4:7], v90 offset:0x6800
	v_add_f32_dpp v0, v0, v0 quad_perm:[1,0,3,2] row_mask:0xf bank_mask:0xf bound_ctrl:1
	v_add_f32_dpp v1, v1, v1 quad_perm:[1,0,3,2] row_mask:0xf bank_mask:0xf bound_ctrl:1
	v_pk_fma_f32 v[54:55], v[52:53], v[8:9], v[10:11]
	v_add_f32_dpp v0, v0, v0 quad_perm:[2,3,0,1] row_mask:0xf bank_mask:0xf bound_ctrl:1
	ds_read_b128 v[8:11], v90 offset:0x2800
	s_nop 0
	v_add_f32_dpp v0, v0, v0 row_half_mirror row_mask:0xf bank_mask:0xf bound_ctrl:1
	s_nop 0
	s_nop 0
	v_add_f32_dpp v2, v0, v0 row_mirror row_mask:0xf bank_mask:0xf bound_ctrl:1
	v_add_f32_dpp v0, v0, v0 row_mirror row_mask:0xf bank_mask:0xf bound_ctrl:1
	ds_read2st64_b32 v[108:109], v89 offset0:212 offset1:213
	s_waitcnt lgkmcnt(3)
	v_permlane16_swap_b32_e32 v0, v2
	v_add_f32_e32 v0, v0, v2
	v_pk_fma_f32 v[52:53], v[104:105], v[0:1], v[54:55] op_sel_hi:[1,0,1]
	v_pk_mul_f32 v[118:119], v[52:53], v[112:113] op_sel_hi:[0,1]
	v_pk_fma_f32 v[118:119], v[52:53], v[114:115], v[118:119] op_sel:[1,0,0]
	v_pk_mul_f32 v[98:99], v[110:111], v[98:99] op_sel:[1,0]
	ds_read_b128 v[112:115], v90 offset:0x6a00
	v_add_f32_dpp v118, v118, v118 quad_perm:[1,0,3,2] row_mask:0xf bank_mask:0xf bound_ctrl:1
	v_add_f32_dpp v119, v119, v119 quad_perm:[1,0,3,2] row_mask:0xf bank_mask:0xf bound_ctrl:1
	v_pk_fma_f32 v[54:55], v[52:53], v[96:97], v[98:99]
	v_add_f32_dpp v118, v118, v118 quad_perm:[2,3,0,1] row_mask:0xf bank_mask:0xf bound_ctrl:1
	ds_read_b128 v[96:99], v90 offset:0x2a00
	s_nop 0
	v_add_f32_dpp v118, v118, v118 row_half_mirror row_mask:0xf bank_mask:0xf bound_ctrl:1
	ds_write2_b32 v93, v1, v119 offset0:72 offset1:108
	s_nop 0
	v_add_f32_dpp v2, v118, v118 row_mirror row_mask:0xf bank_mask:0xf bound_ctrl:1
	v_add_f32_dpp v118, v118, v118 row_mirror row_mask:0xf bank_mask:0xf bound_ctrl:1
	ds_read2st64_b64 v[100:103], v88 offset0:84 offset1:85
	s_waitcnt lgkmcnt(4)
	v_permlane16_swap_b32_e32 v118, v2
	v_add_f32_e32 v118, v118, v2
	v_pk_fma_f32 v[52:53], v[106:107], v[118:119], v[54:55] op_sel_hi:[1,0,1]
	v_pk_mul_f32 v[0:1], v[52:53], v[4:5] op_sel_hi:[0,1]
	v_pk_fma_f32 v[0:1], v[52:53], v[6:7], v[0:1] op_sel:[1,0,0]
	v_pk_mul_f32 v[10:11], v[108:109], v[10:11] op_sel_hi:[0,1]
	ds_read_b128 v[4:7], v90 offset:0x6c00
	v_add_f32_dpp v0, v0, v0 quad_perm:[1,0,3,2] row_mask:0xf bank_mask:0xf bound_ctrl:1
	v_add_f32_dpp v1, v1, v1 quad_perm:[1,0,3,2] row_mask:0xf bank_mask:0xf bound_ctrl:1
	v_pk_fma_f32 v[54:55], v[52:53], v[8:9], v[10:11]
	v_add_f32_dpp v0, v0, v0 quad_perm:[2,3,0,1] row_mask:0xf bank_mask:0xf bound_ctrl:1
	ds_read_b128 v[8:11], v90 offset:0x2c00
	s_nop 0
	v_add_f32_dpp v0, v0, v0 row_half_mirror row_mask:0xf bank_mask:0xf bound_ctrl:1
	s_nop 0
	s_nop 0
	v_add_f32_dpp v2, v0, v0 row_mirror row_mask:0xf bank_mask:0xf bound_ctrl:1
	v_add_f32_dpp v0, v0, v0 row_mirror row_mask:0xf bank_mask:0xf bound_ctrl:1
	ds_read2st64_b32 v[110:111], v89 offset0:214 offset1:215
	s_waitcnt lgkmcnt(3)
	v_permlane16_swap_b32_e32 v0, v2
	v_add_f32_e32 v0, v0, v2
	v_pk_fma_f32 v[52:53], v[100:101], v[0:1], v[54:55] op_sel_hi:[1,0,1]
	v_pk_mul_f32 v[118:119], v[52:53], v[112:113] op_sel_hi:[0,1]
	v_pk_fma_f32 v[118:119], v[52:53], v[114:115], v[118:119] op_sel:[1,0,0]
	v_pk_mul_f32 v[98:99], v[108:109], v[98:99] op_sel:[1,0]
	ds_read_b128 v[112:115], v90 offset:0x6e00
	v_add_f32_dpp v118, v118, v118 quad_perm:[1,0,3,2] row_mask:0xf bank_mask:0xf bound_ctrl:1
	v_add_f32_dpp v119, v119, v119 quad_perm:[1,0,3,2] row_mask:0xf bank_mask:0xf bound_ctrl:1
	v_pk_fma_f32 v[54:55], v[52:53], v[96:97], v[98:99]
	v_add_f32_dpp v118, v118, v118 quad_perm:[2,3,0,1] row_mask:0xf bank_mask:0xf bound_ctrl:1
	ds_read_b128 v[96:99], v90 offset:0x2e00
	s_nop 0
	v_add_f32_dpp v118, v118, v118 row_half_mirror row_mask:0xf bank_mask:0xf bound_ctrl:1
	ds_write2_b32 v93, v1, v119 offset0:144 offset1:180
	s_nop 0
	v_add_f32_dpp v2, v118, v118 row_mirror row_mask:0xf bank_mask:0xf bound_ctrl:1
	v_add_f32_dpp v118, v118, v118 row_mirror row_mask:0xf bank_mask:0xf bound_ctrl:1
	ds_read2st64_b64 v[104:107], v88 offset0:86 offset1:87
	s_waitcnt lgkmcnt(4)
	v_permlane16_swap_b32_e32 v118, v2
	v_add_f32_e32 v118, v118, v2
	v_pk_fma_f32 v[52:53], v[102:103], v[118:119], v[54:55] op_sel_hi:[1,0,1]
	v_pk_mul_f32 v[0:1], v[52:53], v[4:5] op_sel_hi:[0,1]
	v_pk_fma_f32 v[0:1], v[52:53], v[6:7], v[0:1] op_sel:[1,0,0]
	v_pk_mul_f32 v[10:11], v[110:111], v[10:11] op_sel_hi:[0,1]
	ds_read_b128 v[4:7], v90 offset:0x7000
	v_add_f32_dpp v0, v0, v0 quad_perm:[1,0,3,2] row_mask:0xf bank_mask:0xf bound_ctrl:1
	v_add_f32_dpp v1, v1, v1 quad_perm:[1,0,3,2] row_mask:0xf bank_mask:0xf bound_ctrl:1
	v_pk_fma_f32 v[54:55], v[52:53], v[8:9], v[10:11]
	v_add_f32_dpp v0, v0, v0 quad_perm:[2,3,0,1] row_mask:0xf bank_mask:0xf bound_ctrl:1
	ds_read_b128 v[8:11], v90 offset:0x3000
	s_nop 0
	v_add_f32_dpp v0, v0, v0 row_half_mirror row_mask:0xf bank_mask:0xf bound_ctrl:1
	s_nop 0
	s_nop 0
	v_add_f32_dpp v2, v0, v0 row_mirror row_mask:0xf bank_mask:0xf bound_ctrl:1
	v_add_f32_dpp v0, v0, v0 row_mirror row_mask:0xf bank_mask:0xf bound_ctrl:1
	ds_read2st64_b32 v[108:109], v89 offset0:216 offset1:217
	s_waitcnt lgkmcnt(3)
	v_permlane16_swap_b32_e32 v0, v2
	v_add_f32_e32 v0, v0, v2
	v_pk_fma_f32 v[52:53], v[104:105], v[0:1], v[54:55] op_sel_hi:[1,0,1]
	v_pk_mul_f32 v[118:119], v[52:53], v[112:113] op_sel_hi:[0,1]
	v_pk_fma_f32 v[118:119], v[52:53], v[114:115], v[118:119] op_sel:[1,0,0]
	v_pk_mul_f32 v[98:99], v[110:111], v[98:99] op_sel:[1,0]
	ds_read_b128 v[112:115], v90 offset:0x7200
	v_add_f32_dpp v118, v118, v118 quad_perm:[1,0,3,2] row_mask:0xf bank_mask:0xf bound_ctrl:1
	v_add_f32_dpp v119, v119, v119 quad_perm:[1,0,3,2] row_mask:0xf bank_mask:0xf bound_ctrl:1
	v_pk_fma_f32 v[54:55], v[52:53], v[96:97], v[98:99]
	v_add_f32_dpp v118, v118, v118 quad_perm:[2,3,0,1] row_mask:0xf bank_mask:0xf bound_ctrl:1
	ds_read_b128 v[96:99], v90 offset:0x3200
	s_nop 0
	v_add_f32_dpp v118, v118, v118 row_half_mirror row_mask:0xf bank_mask:0xf bound_ctrl:1
	ds_write2_b32 v93, v1, v119 offset0:216 offset1:252
	s_nop 0
	v_add_f32_dpp v2, v118, v118 row_mirror row_mask:0xf bank_mask:0xf bound_ctrl:1
	v_add_f32_dpp v118, v118, v118 row_mirror row_mask:0xf bank_mask:0xf bound_ctrl:1
	ds_read2st64_b64 v[100:103], v88 offset0:88 offset1:89
	s_waitcnt lgkmcnt(4)
	v_permlane16_swap_b32_e32 v118, v2
	v_add_f32_e32 v118, v118, v2
	v_pk_fma_f32 v[52:53], v[106:107], v[118:119], v[54:55] op_sel_hi:[1,0,1]
	v_pk_mul_f32 v[0:1], v[52:53], v[4:5] op_sel_hi:[0,1]
	v_pk_fma_f32 v[0:1], v[52:53], v[6:7], v[0:1] op_sel:[1,0,0]
	v_pk_mul_f32 v[10:11], v[108:109], v[10:11] op_sel_hi:[0,1]
	ds_read_b128 v[4:7], v90 offset:0x7400
	v_add_f32_dpp v0, v0, v0 quad_perm:[1,0,3,2] row_mask:0xf bank_mask:0xf bound_ctrl:1
	v_add_f32_dpp v1, v1, v1 quad_perm:[1,0,3,2] row_mask:0xf bank_mask:0xf bound_ctrl:1
	v_pk_fma_f32 v[54:55], v[52:53], v[8:9], v[10:11]
	v_add_f32_dpp v0, v0, v0 quad_perm:[2,3,0,1] row_mask:0xf bank_mask:0xf bound_ctrl:1
	ds_read_b128 v[8:11], v90 offset:0x3400
	s_nop 0
	v_add_f32_dpp v0, v0, v0 row_half_mirror row_mask:0xf bank_mask:0xf bound_ctrl:1
	v_add_u32_e32 v93, 0x480, v93
	s_nop 0
	v_add_f32_dpp v2, v0, v0 row_mirror row_mask:0xf bank_mask:0xf bound_ctrl:1
	v_add_f32_dpp v0, v0, v0 row_mirror row_mask:0xf bank_mask:0xf bound_ctrl:1
	ds_read2st64_b32 v[110:111], v89 offset0:218 offset1:219
	s_waitcnt lgkmcnt(3)
	v_permlane16_swap_b32_e32 v0, v2
	v_add_f32_e32 v0, v0, v2
	v_pk_fma_f32 v[52:53], v[100:101], v[0:1], v[54:55] op_sel_hi:[1,0,1]
	v_pk_mul_f32 v[118:119], v[52:53], v[112:113] op_sel_hi:[0,1]
	v_pk_fma_f32 v[118:119], v[52:53], v[114:115], v[118:119] op_sel:[1,0,0]
	v_pk_mul_f32 v[98:99], v[108:109], v[98:99] op_sel:[1,0]
	ds_read_b128 v[112:115], v90 offset:0x7600
	v_add_f32_dpp v118, v118, v118 quad_perm:[1,0,3,2] row_mask:0xf bank_mask:0xf bound_ctrl:1
	v_add_f32_dpp v119, v119, v119 quad_perm:[1,0,3,2] row_mask:0xf bank_mask:0xf bound_ctrl:1
	v_pk_fma_f32 v[54:55], v[52:53], v[96:97], v[98:99]
	v_add_f32_dpp v118, v118, v118 quad_perm:[2,3,0,1] row_mask:0xf bank_mask:0xf bound_ctrl:1
	ds_read_b128 v[96:99], v90 offset:0x3600
	s_nop 0
	v_add_f32_dpp v118, v118, v118 row_half_mirror row_mask:0xf bank_mask:0xf bound_ctrl:1
	ds_write2_b32 v93, v1, v119 offset0:0 offset1:36
	s_nop 0
	v_add_f32_dpp v2, v118, v118 row_mirror row_mask:0xf bank_mask:0xf bound_ctrl:1
	v_add_f32_dpp v118, v118, v118 row_mirror row_mask:0xf bank_mask:0xf bound_ctrl:1
	ds_read2st64_b64 v[104:107], v88 offset0:90 offset1:91
	s_waitcnt lgkmcnt(4)
	v_permlane16_swap_b32_e32 v118, v2
	v_add_f32_e32 v118, v118, v2
	v_pk_fma_f32 v[52:53], v[102:103], v[118:119], v[54:55] op_sel_hi:[1,0,1]
	v_pk_mul_f32 v[0:1], v[52:53], v[4:5] op_sel_hi:[0,1]
	v_pk_fma_f32 v[0:1], v[52:53], v[6:7], v[0:1] op_sel:[1,0,0]
	v_pk_mul_f32 v[10:11], v[110:111], v[10:11] op_sel_hi:[0,1]
	ds_read_b128 v[4:7], v90 offset:0x7800
	v_add_f32_dpp v0, v0, v0 quad_perm:[1,0,3,2] row_mask:0xf bank_mask:0xf bound_ctrl:1
	v_add_f32_dpp v1, v1, v1 quad_perm:[1,0,3,2] row_mask:0xf bank_mask:0xf bound_ctrl:1
	v_pk_fma_f32 v[54:55], v[52:53], v[8:9], v[10:11]
	v_add_f32_dpp v0, v0, v0 quad_perm:[2,3,0,1] row_mask:0xf bank_mask:0xf bound_ctrl:1
	ds_read_b128 v[8:11], v90 offset:0x3800
	s_nop 0
	v_add_f32_dpp v0, v0, v0 row_half_mirror row_mask:0xf bank_mask:0xf bound_ctrl:1
	s_nop 0
	s_nop 0
	v_add_f32_dpp v2, v0, v0 row_mirror row_mask:0xf bank_mask:0xf bound_ctrl:1
	v_add_f32_dpp v0, v0, v0 row_mirror row_mask:0xf bank_mask:0xf bound_ctrl:1
	ds_read2st64_b32 v[108:109], v89 offset0:220 offset1:221
	s_waitcnt lgkmcnt(3)
	v_permlane16_swap_b32_e32 v0, v2
	v_add_f32_e32 v0, v0, v2
	v_pk_fma_f32 v[52:53], v[104:105], v[0:1], v[54:55] op_sel_hi:[1,0,1]
	v_pk_mul_f32 v[118:119], v[52:53], v[112:113] op_sel_hi:[0,1]
	v_pk_fma_f32 v[118:119], v[52:53], v[114:115], v[118:119] op_sel:[1,0,0]
	v_pk_mul_f32 v[98:99], v[110:111], v[98:99] op_sel:[1,0]
	ds_read_b128 v[112:115], v90 offset:0x7a00
	v_add_f32_dpp v118, v118, v118 quad_perm:[1,0,3,2] row_mask:0xf bank_mask:0xf bound_ctrl:1
	v_add_f32_dpp v119, v119, v119 quad_perm:[1,0,3,2] row_mask:0xf bank_mask:0xf bound_ctrl:1
	v_pk_fma_f32 v[54:55], v[52:53], v[96:97], v[98:99]
	v_add_f32_dpp v118, v118, v118 quad_perm:[2,3,0,1] row_mask:0xf bank_mask:0xf bound_ctrl:1
	ds_read_b128 v[96:99], v90 offset:0x3a00
	s_nop 0
	v_add_f32_dpp v118, v118, v118 row_half_mirror row_mask:0xf bank_mask:0xf bound_ctrl:1
	ds_write2_b32 v93, v1, v119 offset0:72 offset1:108
	s_nop 0
	v_add_f32_dpp v2, v118, v118 row_mirror row_mask:0xf bank_mask:0xf bound_ctrl:1
	v_add_f32_dpp v118, v118, v118 row_mirror row_mask:0xf bank_mask:0xf bound_ctrl:1
	ds_read2st64_b64 v[100:103], v88 offset0:92 offset1:93
	s_waitcnt lgkmcnt(4)
	v_permlane16_swap_b32_e32 v118, v2
	v_add_f32_e32 v118, v118, v2
	v_pk_fma_f32 v[52:53], v[106:107], v[118:119], v[54:55] op_sel_hi:[1,0,1]
	v_pk_mul_f32 v[0:1], v[52:53], v[4:5] op_sel_hi:[0,1]
	v_pk_fma_f32 v[0:1], v[52:53], v[6:7], v[0:1] op_sel:[1,0,0]
	v_pk_mul_f32 v[10:11], v[108:109], v[10:11] op_sel_hi:[0,1]
	ds_read_b128 v[4:7], v90 offset:0x7c00
	v_add_f32_dpp v0, v0, v0 quad_perm:[1,0,3,2] row_mask:0xf bank_mask:0xf bound_ctrl:1
	v_add_f32_dpp v1, v1, v1 quad_perm:[1,0,3,2] row_mask:0xf bank_mask:0xf bound_ctrl:1
	v_pk_fma_f32 v[54:55], v[52:53], v[8:9], v[10:11]
	v_add_f32_dpp v0, v0, v0 quad_perm:[2,3,0,1] row_mask:0xf bank_mask:0xf bound_ctrl:1
	ds_read_b128 v[8:11], v90 offset:0x3c00
	s_nop 0
	v_add_f32_dpp v0, v0, v0 row_half_mirror row_mask:0xf bank_mask:0xf bound_ctrl:1
	s_nop 0
	s_nop 0
	v_add_f32_dpp v2, v0, v0 row_mirror row_mask:0xf bank_mask:0xf bound_ctrl:1
	v_add_f32_dpp v0, v0, v0 row_mirror row_mask:0xf bank_mask:0xf bound_ctrl:1
	ds_read2st64_b32 v[110:111], v89 offset0:222 offset1:223
	s_waitcnt lgkmcnt(3)
	v_permlane16_swap_b32_e32 v0, v2
	v_add_f32_e32 v0, v0, v2
	v_pk_fma_f32 v[52:53], v[100:101], v[0:1], v[54:55] op_sel_hi:[1,0,1]
	v_pk_mul_f32 v[118:119], v[52:53], v[112:113] op_sel_hi:[0,1]
	v_pk_fma_f32 v[118:119], v[52:53], v[114:115], v[118:119] op_sel:[1,0,0]
	v_pk_mul_f32 v[98:99], v[108:109], v[98:99] op_sel:[1,0]
	ds_read_b128 v[112:115], v90 offset:0x7e00
	v_add_f32_dpp v118, v118, v118 quad_perm:[1,0,3,2] row_mask:0xf bank_mask:0xf bound_ctrl:1
	v_add_f32_dpp v119, v119, v119 quad_perm:[1,0,3,2] row_mask:0xf bank_mask:0xf bound_ctrl:1
	v_pk_fma_f32 v[54:55], v[52:53], v[96:97], v[98:99]
	v_add_f32_dpp v118, v118, v118 quad_perm:[2,3,0,1] row_mask:0xf bank_mask:0xf bound_ctrl:1
	ds_read_b128 v[96:99], v90 offset:0x3e00
	s_nop 0
	v_add_f32_dpp v118, v118, v118 row_half_mirror row_mask:0xf bank_mask:0xf bound_ctrl:1
	ds_write2_b32 v93, v1, v119 offset0:144 offset1:180
	s_nop 0
	v_add_f32_dpp v2, v118, v118 row_mirror row_mask:0xf bank_mask:0xf bound_ctrl:1
	v_add_f32_dpp v118, v118, v118 row_mirror row_mask:0xf bank_mask:0xf bound_ctrl:1
	ds_read2st64_b64 v[104:107], v88 offset0:94 offset1:95
	s_waitcnt lgkmcnt(4)
	v_permlane16_swap_b32_e32 v118, v2
	v_add_f32_e32 v118, v118, v2
	v_pk_fma_f32 v[52:53], v[102:103], v[118:119], v[54:55] op_sel_hi:[1,0,1]
	v_pk_mul_f32 v[0:1], v[52:53], v[4:5] op_sel_hi:[0,1]
	v_pk_fma_f32 v[0:1], v[52:53], v[6:7], v[0:1] op_sel:[1,0,0]
	v_pk_mul_f32 v[10:11], v[110:111], v[10:11] op_sel_hi:[0,1]
	s_nop 0
	v_add_f32_dpp v0, v0, v0 quad_perm:[1,0,3,2] row_mask:0xf bank_mask:0xf bound_ctrl:1
	v_add_f32_dpp v1, v1, v1 quad_perm:[1,0,3,2] row_mask:0xf bank_mask:0xf bound_ctrl:1
	v_pk_fma_f32 v[54:55], v[52:53], v[8:9], v[10:11]
	v_add_f32_dpp v0, v0, v0 quad_perm:[2,3,0,1] row_mask:0xf bank_mask:0xf bound_ctrl:1
	s_nop 0
	s_nop 0
	v_add_f32_dpp v0, v0, v0 row_half_mirror row_mask:0xf bank_mask:0xf bound_ctrl:1
	s_nop 0
	s_nop 0
	v_add_f32_dpp v2, v0, v0 row_mirror row_mask:0xf bank_mask:0xf bound_ctrl:1
	v_add_f32_dpp v0, v0, v0 row_mirror row_mask:0xf bank_mask:0xf bound_ctrl:1
	s_nop 0
	s_waitcnt lgkmcnt(0)
	v_permlane16_swap_b32_e32 v0, v2
	v_add_f32_e32 v0, v0, v2
	v_pk_fma_f32 v[52:53], v[104:105], v[0:1], v[54:55] op_sel_hi:[1,0,1]
	v_pk_mul_f32 v[118:119], v[52:53], v[112:113] op_sel_hi:[0,1]
	v_pk_fma_f32 v[118:119], v[52:53], v[114:115], v[118:119] op_sel:[1,0,0]
	v_pk_mul_f32 v[98:99], v[110:111], v[98:99] op_sel:[1,0]
	s_nop 0
	v_add_f32_dpp v118, v118, v118 quad_perm:[1,0,3,2] row_mask:0xf bank_mask:0xf bound_ctrl:1
	v_add_f32_dpp v119, v119, v119 quad_perm:[1,0,3,2] row_mask:0xf bank_mask:0xf bound_ctrl:1
	v_pk_fma_f32 v[54:55], v[52:53], v[96:97], v[98:99]
	v_add_f32_dpp v118, v118, v118 quad_perm:[2,3,0,1] row_mask:0xf bank_mask:0xf bound_ctrl:1
	s_nop 0
	s_nop 0
	v_add_f32_dpp v118, v118, v118 row_half_mirror row_mask:0xf bank_mask:0xf bound_ctrl:1
	ds_write2_b32 v93, v1, v119 offset0:216 offset1:252
	s_nop 0
	v_add_f32_dpp v2, v118, v118 row_mirror row_mask:0xf bank_mask:0xf bound_ctrl:1
	v_add_f32_dpp v118, v118, v118 row_mirror row_mask:0xf bank_mask:0xf bound_ctrl:1
	s_nop 0
	s_nop 0
	v_permlane16_swap_b32_e32 v118, v2
	v_add_f32_e32 v118, v118, v2
	v_pk_fma_f32 v[52:53], v[106:107], v[118:119], v[54:55] op_sel_hi:[1,0,1]
